# v42 plus retention chunk-state phase with three LDS stages: operand DMA two items ahead, barrier waits for the older DMA group only
# speedup vs baseline: 1.0119x; 1.0119x over previous
; __device__ __forceinline__ s16x4 vtr(ldsp p) { typedef short v4i16_t __attribute__((ext_vector_type(4))); return __builtin_bit_cast(s16x4, __builtin_amdgcn_ds_read_tr16_b64_v4i16((ALDS v4i16_t*)p)); }
; __device__ __forceinline__ void wait_all_barrier() { asm volatile("s_waitcnt vmcnt(0) lgkmcnt(0)\n\ts_barrier" ::: "memory"); }
; __device__ __forceinline__ bf16x8 tr_nat(unsigned img, int c, int ks, int lane) {
;     const unsigned hh = lane >> 5, blk = (lane >> 4) & 1, qq = (lane & 15) >> 2, p = lane & 3;
;     const unsigned row0 = 16u * ks + 8u * hh + qq, ch = 4u * c + 2u * blk + (p >> 1);
;     const s16x4 lo = vtr((ldsp)(size_t)(img + off_b(row0, ch) + 8u * (p & 1u))), hi = vtr((ldsp)(size_t)(img + off_b(row0 + 4u, ch) + 8u * (p & 1u)));
; __device__ __forceinline__ void r1_phase(ldsp lds, const bf16* U, bf16* KV, int G, int bx, int wave, int lane) {
;     const unsigned lds0 = (unsigned)(size_t)lds;
;     const int dt = wave & 1, et = wave >> 1, r = lane & 31, hh = lane >> 5;
;     if (bx < N_ITEMS) stage_item<false>(lds, 0, bx, U, nullptr, wave, lane);
;     wait_all_barrier();
;     int k = 0;
;     for (int item = bx; item < N_ITEMS; item += G, ++k) {
;         const unsigned st = lds0 + (k & 1) * STAGE;
;         if (item + G < N_ITEMS) stage_item<false>(lds, ((k + 1) & 1) * STAGE, item + G, U, nullptr, wave, lane);
;         int b, n, h; decode(item, b, n, h);
;         const float lg2 = log2f(1.0f - exp2f(-5.0f - (float)h));
;         f32x16 acc;
; #pragma unroll
;         for (int i = 0; i < 16; ++i) acc[i] = 0.f;
; #pragma unroll
;         for (int ks = 0; ks < 4; ++ks) {
;             const bf16x8 kf = tr_nat(st, dt, ks, lane), vf = tr_nat(st + 16384, et, ks, lane);
;             float kd[8];
; #pragma unroll
;             for (int jj = 0; jj < 8; ++jj) kd[jj] = bfs(kf[jj]) * __builtin_amdgcn_exp2f(lg2 * (float)(63 - (16 * ks + 8 * hh + jj)));
.LBB0_237:
	s_waitcnt vmcnt(0) lgkmcnt(0)
	s_barrier
	v_cndmask_b32_e64 v2, 0, 1, s[4:5]
	s_bfe_u32 s6, s0, 0x10006
	s_lshr_b32 s87, s86, 1
	v_cmp_ne_u32_e64 s[8:9], 1, v2
	s_andn2_b64 vcc, exec, s[4:5]
	s_cbranch_vccnz .LBB0_242
	s_lshl_b32 s7, s86, 1
	v_lshrrev_b32_e32 v4, 4, v0
	s_and_b32 s1, s7, 2
	s_or_b32 s7, s7, 1
	v_and_b32_e32 v2, 15, v1
	v_lshlrev_b32_e32 v3, 2, v4
	s_and_b32 s10, s7, 3
	v_bitop3_b32 v5, v3, v2, s1 bitop3:0x36
	v_bitop3_b32 v2, v3, v2, s10 bitop3:0x36
	v_cmp_gt_u32_e64 s[10:11], 8, v2
	v_lshlrev_b32_e32 v22, 3, v2
	v_lshrrev_b32_e32 v2, 3, v1
	v_cmp_gt_u32_e64 s[4:5], 8, v5
	v_lshlrev_b32_e32 v20, 3, v5
	v_lshrrev_b32_e32 v5, 2, v0
	v_and_b32_e32 v2, 2, v2
	v_and_b32_e32 v6, 11, v5
	v_lshl_or_b32 v7, s6, 2, v2
	v_bfe_u32 v8, v1, 1, 1
	v_lshl_or_b32 v10, s87, 2, v2
	v_or_b32_e32 v3, v7, v8
	v_and_b32_e32 v1, 12, v1
	v_lshrrev_b32_e32 v9, 2, v6
	v_or_b32_e32 v2, v10, v8
	v_bitop3_b32 v3, v9, v3, v1 bitop3:0x36
	v_bitop3_b32 v2, v9, v2, v1 bitop3:0x36
	v_or3_b32 v1, v1, v4, 1
	v_lshl_or_b32 v16, s86, 3, v4
	v_lshl_or_b32 v24, s7, 2, v4
	v_bitop3_b32 v4, v7, v1, v8 bitop3:0x36
	v_bitop3_b32 v7, v5, 63, 8 bitop3:0x6c
	v_cvt_f32_ubyte0_e32 v33, v7
	v_bitop3_b32 v7, v5, 62, 8 bitop3:0x6c
	v_cvt_f32_ubyte0_e32 v34, v7
	v_bitop3_b32 v7, v5, 61, 8 bitop3:0x6c
	v_cvt_f32_ubyte0_e32 v35, v7
	v_bitop3_b32 v7, v5, 60, 8 bitop3:0x6c
	v_cvt_f32_ubyte0_e32 v36, v7
	v_bitop3_b32 v7, v5, 59, 8 bitop3:0x6c
	v_cvt_f32_ubyte0_e32 v37, v7
	v_bitop3_b32 v7, v5, 58, 8 bitop3:0x6c
	v_cvt_f32_ubyte0_e32 v38, v7
	v_bitop3_b32 v7, v5, 57, 8 bitop3:0x6c
	v_lshlrev_b32_e32 v30, 8, v6
	v_lshlrev_b32_e32 v6, 8, v5
	v_bitop3_b32 v1, v10, v1, v8 bitop3:0x36
	v_cvt_f32_ubyte0_e32 v39, v7
	v_bitop3_b32 v7, v5, 56, 8 bitop3:0x6c
	v_lshlrev_b32_e32 v4, 4, v4
	v_lshlrev_b32_e32 v1, 4, v1
	v_cvt_f32_ubyte0_e32 v40, v7
	v_or_b32_e32 v7, 0x1400, v6
	v_or_b32_e32 v42, v4, v7
	v_or_b32_e32 v43, v1, v7
	v_bitop3_b32 v7, v5, 47, 8 bitop3:0x6c
	v_cvt_f32_ubyte0_e32 v44, v7
	v_bitop3_b32 v7, v5, 46, 8 bitop3:0x6c
	v_cvt_f32_ubyte0_e32 v45, v7
	v_bitop3_b32 v7, v5, 45, 8 bitop3:0x6c
	v_cvt_f32_ubyte0_e32 v46, v7
	v_bitop3_b32 v7, v5, 44, 8 bitop3:0x6c
	v_cvt_f32_ubyte0_e32 v47, v7
	v_bitop3_b32 v7, v5, 43, 8 bitop3:0x6c
	v_cvt_f32_ubyte0_e32 v48, v7
	v_bitop3_b32 v7, v5, 42, 8 bitop3:0x6c
	v_cvt_f32_ubyte0_e32 v49, v7
	v_bitop3_b32 v7, v5, 41, 8 bitop3:0x6c
	v_cvt_f32_ubyte0_e32 v50, v7
	v_bitop3_b32 v7, v5, 40, 8 bitop3:0x6c
	v_or_b32_e32 v9, 0x400, v6
	v_cvt_f32_ubyte0_e32 v51, v7
	v_or_b32_e32 v7, 0x2400, v6
	v_or_b32_e32 v6, 0x3400, v6
	v_or_b32_e32 v32, v1, v9
	v_or_b32_e32 v54, v1, v7
	v_or_b32_e32 v65, v1, v6
	v_bitop3_b32 v1, v5, 15, 8 bitop3:0x6c
	v_cvt_f32_ubyte0_e32 v66, v1
	v_bitop3_b32 v1, v5, 14, 8 bitop3:0x6c
	v_or_b32_e32 v53, v4, v7
	v_bitop3_b32 v7, v5, 31, 8 bitop3:0x6c
	v_cvt_f32_ubyte0_e32 v67, v1
	v_bitop3_b32 v1, v5, 13, 8 bitop3:0x6c
	v_cvt_f32_ubyte0_e32 v55, v7
	v_bitop3_b32 v7, v5, 30, 8 bitop3:0x6c
	v_cvt_f32_ubyte0_e32 v68, v1
	v_bitop3_b32 v1, v5, 12, 8 bitop3:0x6c
	s_lshl_b32 s3, s86, 11
	s_lshl_b32 s7, s7, 10
	s_lshl_b32 s16, s87, 6
	v_cvt_f32_ubyte0_e32 v56, v7
	v_bitop3_b32 v7, v5, 29, 8 bitop3:0x6c
	v_cvt_f32_ubyte0_e32 v69, v1
	v_bitop3_b32 v1, v5, 11, 8 bitop3:0x6c
	v_lshlrev_b32_e32 v17, 4, v3
	v_lshlrev_b32_e32 v3, 3, v0
	s_add_u32 s14, s14, s16
	v_cvt_f32_ubyte0_e32 v57, v7
	v_bitop3_b32 v7, v5, 28, 8 bitop3:0x6c
	v_cvt_f32_ubyte0_e32 v70, v1
	v_bitop3_b32 v1, v5, 10, 8 bitop3:0x6c
	v_lshlrev_b32_e32 v0, 8, v0
	v_mov_b32_e32 v19, 0
	s_addc_u32 s15, s15, 0
	v_and_b32_e32 v18, 8, v5
	v_cvt_f32_ubyte0_e32 v58, v7
	v_bitop3_b32 v7, v5, 27, 8 bitop3:0x6c
	v_cvt_f32_ubyte0_e32 v71, v1
	v_bitop3_b32 v1, v5, 9, 8 bitop3:0x6c
	v_and_b32_e32 v0, 0x1f00, v0
	v_and_b32_e32 v25, 8, v3
	v_lshlrev_b32_e32 v28, 4, v2
	v_lshl_add_u64 v[2:3], s[14:15], 0, v[18:19]
	v_cvt_f32_ubyte0_e32 v59, v7
	v_bitop3_b32 v7, v5, 26, 8 bitop3:0x6c
	v_cvt_f32_ubyte0_e32 v72, v1
	v_bitop3_b32 v1, v5, 8, v5 bitop3:0xc
	v_lshl_or_b32 v18, s6, 13, v0
	v_cvt_f32_ubyte0_e32 v60, v7
	v_bitop3_b32 v7, v5, 25, 8 bitop3:0x6c
	v_cvt_f32_ubyte0_e32 v73, v1
	v_lshl_add_u64 v[0:1], v[2:3], 0, v[18:19]
	s_mov_b64 s[14:15], 0xfa00000
	v_cvt_f32_ubyte0_e32 v61, v7
	v_bitop3_b32 v7, v5, 24, 8 bitop3:0x6c
	v_lshl_add_u64 v[26:27], v[0:1], 0, s[14:15]
	s_add_i32 s14, s28, s2
	s_mov_b32 s1, 0
	v_mov_b32_e32 v21, v19
	v_mov_b32_e32 v23, v19
	v_or_b32_e32 v29, 0x4000, v25
	v_or_b32_e32 v31, v4, v9
	v_or_b32_e32 v41, 0x1000, v30
	s_movk_i32 s22, 0x1400
	v_or_b32_e32 v52, 0x2000, v30
	v_cvt_f32_ubyte0_e32 v62, v7
	v_or_b32_e32 v63, 0x3000, v30
	v_or_b32_e32 v64, v4, v6
	s_lshl_b32 s23, s14, 6
	s_lshl_b32 s24, s28, 6
	s_lshl_b32 s25, s14, 7
	s_lshl_b32 s26, s28, 7
	s_mov_b64 s[14:15], 0x600
	s_add_i32 s27, 0, 0xc000
	s_mov_b32 s30, 0xc2fc0000
	s_mov_b32 s31, 0x800000
	v_mov_b32_e32 v74, 0x1400
	v_not_b32_e32 v75, 63
	v_mov_b32_e32 v76, 0x180
	v_mov_b32_e32 v77, 0x42800000
	v_mov_b32_e32 v78, 0x42000000
	s_mov_b32 s18, s2
	s_mov_b32 s98, 0
	s_branch .LBB0_240
; __device__ __forceinline__ unsigned cvtpk(float lo, float hi) { f32x2_t v = {lo, hi}; bf16x2_t b = __builtin_convertvector(v, bf16x2_t); return __builtin_bit_cast(unsigned, b); }
; __device__ __forceinline__ void wait_all_barrier() { asm volatile("s_waitcnt vmcnt(0) lgkmcnt(0)\n\ts_barrier" ::: "memory"); }
; __device__ __forceinline__ void r1_phase(ldsp lds, const bf16* U, bf16* KV, int G, int bx, int wave, int lane) {
;     ...
;         int b, n, h; decode(item, b, n, h);
;         const float lg2 = log2f(1.0f - exp2f(-5.0f - (float)h));
;         f32x16 acc;
; #pragma unroll
;         for (int i = 0; i < 16; ++i) acc[i] = 0.f;
; #pragma unroll
;         for (int ks = 0; ks < 4; ++ks) {
;             const bf16x8 kf = tr_nat(st, dt, ks, lane), vf = tr_nat(st + 16384, et, ks, lane);
;             float kd[8];
; #pragma unroll
;             for (int jj = 0; jj < 8; ++jj) kd[jj] = bfs(kf[jj]) * __builtin_amdgcn_exp2f(lg2 * (float)(63 - (16 * ks + 8 * hh + jj)));
;             typedef unsigned u4 __attribute__((ext_vector_type(4)));
;             u4 w; w.x = cvtpk(kd[0], kd[1]); w.y = cvtpk(kd[2], kd[3]); w.z = cvtpk(kd[4], kd[5]); w.w = cvtpk(kd[6], kd[7]);
;             acc = __builtin_amdgcn_mfma_f32_32x32x16_bf16(vf, __builtin_bit_cast(bf16x8, w), acc, 0, 0, 0);
;         }
;         wait_all_barrier();
.LBB0_239:
	s_nop 0
	s_mul_hi_i32 s34, s18, 0x2aaaaaab
	s_mov_b32 s19, s98
	s_lshr_b32 s35, s34, 31
	s_add_i32 s34, s34, s35
	s_mul_i32 s34, s34, 6
	s_sub_i32 s34, s18, s34
	v_cvt_f32_i32_e32 v0, s34
	v_or_b32_e32 v18, s19, v25
	v_add_u32_e32 v96, v18, v17
	v_add_u32_e32 v79, s19, v29
	v_sub_f32_e32 v0, 0xc0a00000, v0
	v_cmp_gt_f32_e32 vcc, s30, v0
	s_and_b64 s[34:35], vcc, exec
	s_cselect_b32 s34, 0xffffffc0, 0
	v_cndmask_b32_e32 v1, 0, v77, vcc
	v_add_f32_e32 v0, v0, v1
	v_exp_f32_e32 v0, v0
	v_add_u32_e32 v80, v96, v41
	v_add_u32_e32 v98, v79, v28
	ds_read_b64_tr_b16 v[84:85], v80
	v_ldexp_f32 v0, v0, s34
	v_sub_f32_e32 v0, 1.0, v0
	v_cmp_gt_f32_e32 vcc, s31, v0
	s_and_b64 s[34:35], vcc, exec
	s_cselect_b32 s34, 32, 0
	v_ldexp_f32 v0, v0, s34
	v_log_f32_e32 v0, v0
	v_cndmask_b32_e32 v1, 0, v78, vcc
	v_add_u32_e32 v2, v32, v79
	ds_read_b64_tr_b16 v[2:3], v2
	v_sub_f32_e32 v97, v0, v1
	v_add_u32_e32 v0, v96, v30
	ds_read_b64_tr_b16 v[4:5], v0
	v_add_u32_e32 v0, v31, v18
	v_mul_f32_e32 v8, v97, v33
	v_mul_f32_e32 v9, v97, v34
	ds_read_b64_tr_b16 v[6:7], v0
	s_waitcnt lgkmcnt(1)
	v_and_b32_e32 v11, 0xffff0000, v4
	v_lshlrev_b32_e32 v10, 16, v4
	v_mul_f32_e32 v4, v97, v35
	v_exp_f32_e32 v8, v8
	v_exp_f32_e32 v9, v9
	v_exp_f32_e32 v12, v4
	v_mul_f32_e32 v4, v97, v36
	v_exp_f32_e32 v13, v4
	v_add_u32_e32 v0, v98, v30
	ds_read_b64_tr_b16 v[0:1], v0
	v_pk_mul_f32 v[8:9], v[8:9], v[10:11]
	v_and_b32_e32 v11, 0xffff0000, v5
	v_lshlrev_b32_e32 v10, 16, v5
	v_pk_mul_f32 v[10:11], v[12:13], v[10:11]
	v_mul_f32_e32 v4, v97, v37
	v_mul_f32_e32 v5, v97, v38
	s_waitcnt lgkmcnt(1)
	v_and_b32_e32 v13, 0xffff0000, v6
	v_lshlrev_b32_e32 v12, 16, v6
	v_mul_f32_e32 v6, v97, v39
	v_exp_f32_e32 v4, v4
	v_exp_f32_e32 v5, v5
	v_exp_f32_e32 v14, v6
	v_mul_f32_e32 v6, v97, v40
	v_exp_f32_e32 v15, v6
	v_add_u32_e32 v80, v42, v18
	v_mul_f32_e32 v88, v97, v44
	v_mul_f32_e32 v89, v97, v45
	v_and_b32_e32 v91, 0xffff0000, v84
	v_lshlrev_b32_e32 v90, 16, v84
	v_mul_f32_e32 v84, v97, v46
	ds_read_b64_tr_b16 v[86:87], v80
	v_exp_f32_e32 v88, v88
	v_exp_f32_e32 v89, v89
	v_exp_f32_e32 v92, v84
	v_mul_f32_e32 v84, v97, v47
	v_exp_f32_e32 v93, v84
	v_pk_mul_f32 v[12:13], v[4:5], v[12:13]
	v_and_b32_e32 v5, 0xffff0000, v7
	v_lshlrev_b32_e32 v4, 16, v7
	v_pk_mul_f32 v[14:15], v[14:15], v[4:5]
	v_add_u32_e32 v80, v98, v41
	v_add_u32_e32 v82, v43, v79
	v_cvt_pk_bf16_f32 v4, v8, v9
	v_cvt_pk_bf16_f32 v5, v10, v11
	v_cvt_pk_bf16_f32 v6, v12, v13
	v_cvt_pk_bf16_f32 v7, v14, v15
	ds_read_b64_tr_b16 v[80:81], v80
	ds_read_b64_tr_b16 v[82:83], v82
	v_pk_mul_f32 v[88:89], v[88:89], v[90:91]
	v_and_b32_e32 v91, 0xffff0000, v85
	v_lshlrev_b32_e32 v90, 16, v85
	s_waitcnt lgkmcnt(3)
	v_mfma_f32_32x32x16_bf16 v[0:15], v[0:3], v[4:7], 0
	v_mul_f32_e64 v90, v92, v90
	v_mul_f32_e64 v91, v93, v91
	v_mul_f32_e32 v84, v97, v48
	v_mul_f32_e32 v85, v97, v49
	s_waitcnt lgkmcnt(2)
	v_and_b32_e32 v93, 0xffff0000, v86
	v_lshlrev_b32_e32 v92, 16, v86
	v_mul_f32_e32 v86, v97, v50
	v_exp_f32_e32 v84, v84
	v_exp_f32_e32 v85, v85
	v_exp_f32_e32 v94, v86
	v_mul_f32_e32 v86, v97, v51
	v_exp_f32_e32 v95, v86
	v_pk_mul_f32 v[92:93], v[84:85], v[92:93]
	v_and_b32_e32 v85, 0xffff0000, v87
	v_lshlrev_b32_e32 v84, 16, v87
	v_pk_mul_f32 v[94:95], v[94:95], v[84:85]
	v_cvt_pk_bf16_f32 v84, v88, v89
	v_cvt_pk_bf16_f32 v85, v90, v91
	v_cvt_pk_bf16_f32 v86, v92, v93
	v_cvt_pk_bf16_f32 v87, v94, v95
	v_mul_f32_e32 v88, v97, v55
	v_mul_f32_e32 v89, v97, v56
	s_waitcnt lgkmcnt(0)
	v_mfma_f32_32x32x16_bf16 v[0:15], v[80:83], v[84:87], v[0:15]
	v_add_u32_e32 v80, v96, v52
	ds_read_b64_tr_b16 v[84:85], v80
	v_add_u32_e32 v80, v53, v18
	ds_read_b64_tr_b16 v[86:87], v80
	v_exp_f32_e32 v88, v88
	v_exp_f32_e32 v89, v89
	s_waitcnt lgkmcnt(1)
	v_and_b32_e32 v91, 0xffff0000, v84
	v_lshlrev_b32_e32 v90, 16, v84
	v_mul_f32_e32 v84, v97, v57
	v_exp_f32_e32 v92, v84
	v_mul_f32_e32 v84, v97, v58
	v_exp_f32_e32 v93, v84
	v_add_u32_e32 v80, v98, v52
	v_add_u32_e32 v82, v54, v79
	ds_read_b64_tr_b16 v[80:81], v80
	ds_read_b64_tr_b16 v[82:83], v82
	v_pk_mul_f32 v[88:89], v[88:89], v[90:91]
	v_and_b32_e32 v91, 0xffff0000, v85
	v_lshlrev_b32_e32 v90, 16, v85
	v_pk_mul_f32 v[90:91], v[92:93], v[90:91]
	v_mul_f32_e32 v84, v97, v59
	v_mul_f32_e32 v85, v97, v60
	s_waitcnt lgkmcnt(2)
	v_and_b32_e32 v93, 0xffff0000, v86
	v_lshlrev_b32_e32 v92, 16, v86
	v_mul_f32_e32 v86, v97, v61
	v_exp_f32_e32 v84, v84
	v_exp_f32_e32 v85, v85
	v_exp_f32_e32 v94, v86
	v_mul_f32_e32 v86, v97, v62
	v_exp_f32_e32 v95, v86
	v_pk_mul_f32 v[92:93], v[84:85], v[92:93]
	v_and_b32_e32 v85, 0xffff0000, v87
	v_lshlrev_b32_e32 v84, 16, v87
	v_pk_mul_f32 v[94:95], v[94:95], v[84:85]
	v_cvt_pk_bf16_f32 v84, v88, v89
	v_cvt_pk_bf16_f32 v85, v90, v91
	v_cvt_pk_bf16_f32 v86, v92, v93
	v_cvt_pk_bf16_f32 v87, v94, v95
	v_add_u32_e32 v18, v64, v18
	s_ashr_i32 s19, s18, 31
	s_waitcnt lgkmcnt(0)
	v_mfma_f32_32x32x16_bf16 v[0:15], v[80:83], v[84:87], v[0:15]
	v_add_u32_e32 v80, v96, v63
	ds_read_b64_tr_b16 v[86:87], v18
	v_add_u32_e32 v18, v98, v63
	ds_read_b64_tr_b16 v[84:85], v80
	ds_read_b64_tr_b16 v[80:81], v18
	v_add_u32_e32 v18, v65, v79
	ds_read_b64_tr_b16 v[82:83], v18
	v_mul_f32_e32 v18, v97, v66
	v_exp_f32_e32 v88, v18
	v_mul_f32_e32 v18, v97, v67
	v_exp_f32_e32 v89, v18
	v_mul_f32_e32 v18, v97, v68
	v_exp_f32_e32 v92, v18
	v_mul_f32_e32 v18, v97, v69
	v_exp_f32_e32 v93, v18
	v_mul_f32_e32 v18, v97, v70
	s_waitcnt lgkmcnt(2)
	v_and_b32_e32 v91, 0xffff0000, v84
	v_lshlrev_b32_e32 v90, 16, v84
	v_exp_f32_e32 v84, v18
	v_mul_f32_e32 v18, v97, v71
	v_pk_mul_f32 v[88:89], v[88:89], v[90:91]
	v_and_b32_e32 v91, 0xffff0000, v85
	v_lshlrev_b32_e32 v90, 16, v85
	v_exp_f32_e32 v85, v18
	v_mul_f32_e32 v18, v97, v72
	v_exp_f32_e32 v94, v18
	v_mul_f32_e32 v18, v97, v73
	v_exp_f32_e32 v95, v18
	v_pk_mul_f32 v[90:91], v[92:93], v[90:91]
	v_and_b32_e32 v93, 0xffff0000, v86
	v_lshlrev_b32_e32 v92, 16, v86
	v_pk_mul_f32 v[92:93], v[84:85], v[92:93]
	v_and_b32_e32 v85, 0xffff0000, v87
	v_lshlrev_b32_e32 v84, 16, v87
	v_pk_mul_f32 v[94:95], v[94:95], v[84:85]
	v_cvt_pk_bf16_f32 v84, v88, v89
	v_cvt_pk_bf16_f32 v85, v90, v91
	v_cvt_pk_bf16_f32 v86, v92, v93
	v_cvt_pk_bf16_f32 v87, v94, v95
	s_lshl_b64 s[18:19], s[18:19], 14
	s_add_i32 s34, s33, s28
	s_cmpk_gt_i32 s34, 0x5ff
	s_cbranch_scc1 .Lr1a_w0
	s_waitcnt vmcnt(4) lgkmcnt(0)
	s_branch .Lr1a_wb

; __device__ __forceinline__ unsigned cvtpk(float lo, float hi) { f32x2_t v = {lo, hi}; bf16x2_t b = __builtin_convertvector(v, bf16x2_t); return __builtin_bit_cast(unsigned, b); }
; __device__ __forceinline__ void wait_all_barrier() { asm volatile("s_waitcnt vmcnt(0) lgkmcnt(0)\n\ts_barrier" ::: "memory"); }
; template <bool WITH_PREV>
; __device__ __forceinline__ void stage_item(ldsp lds, int stage, int item, const bf16* U, const bf16* PREV, int wave, int lane) {
;     int b, n, h; decode(item, b, n, h);
;     const int prow = lane >> 4, chp = lane & 15;
; #pragma unroll
;     for (int i = 0; i < 2; ++i) { const int pi = wave * 2 + i, row = 4 * pi + prow; const unsigned ch = (unsigned)chp ^ (((unsigned)prow << 2) | ((unsigned)pi & 3u));
;         const bf16* urow = U + ((size_t)b * SEQ + 64 * n + row) * INW;
;         dma16(urow + (ch < 8u ? 384 + h * 64 + ch * 8 : h * 64 + (ch - 8u) * 8), lds + stage + 1024 * pi);
;         dma16(urow + 768 + h * 128 + ch * 8, lds + stage + 16384 + 1024 * pi);
;         if (WITH_PREV) dma16(PREV + ((size_t)item * 64 + row) * 128 + ch * 8, lds + stage + 32768 + 1024 * pi); }
; }
; __device__ __forceinline__ void r1_phase(ldsp lds, const bf16* U, bf16* KV, int G, int bx, int wave, int lane) {
;     const unsigned lds0 = (unsigned)(size_t)lds;
;     const int dt = wave & 1, et = wave >> 1, r = lane & 31, hh = lane >> 5;
;     if (bx < N_ITEMS) stage_item<false>(lds, 0, bx, U, nullptr, wave, lane);
;     wait_all_barrier();
;     int k = 0;
;     for (int item = bx; item < N_ITEMS; item += G, ++k) {
;         const unsigned st = lds0 + (k & 1) * STAGE;
;         if (item + G < N_ITEMS) stage_item<false>(lds, ((k + 1) & 1) * STAGE, item + G, U, nullptr, wave, lane);
;     ...
;         wait_all_barrier();
;         bf16* kvp = KV + ((size_t)item * 64 + 32 * dt + r) * 128 + 32 * et + 4 * hh;
; #pragma unroll
;         for (int g4 = 0; g4 < 4; ++g4) { v2u pk; pk.x = cvtpk(acc[4 * g4], acc[4 * g4 + 1]); pk.y = cvtpk(acc[4 * g4 + 2], acc[4 * g4 + 3]); *(v2u*)(kvp + 8 * g4) = pk; }
;     }
.Lr1a_wb:
	s_barrier
	s_add_i32 s1, s1, 1
	s_add_i32 s98, s98, 0xc000
	s_cmp_eq_u32 s98, 0x24000
	s_cselect_b32 s98, 0, s98
	s_waitcnt lgkmcnt(0)
	v_mfma_f32_32x32x16_bf16 v[0:15], v[80:83], v[84:87], v[0:15]
	v_lshl_add_u64 v[80:81], v[26:27], 0, s[18:19]
	s_add_i32 s23, s23, s24
	s_add_i32 s25, s25, s26
	s_andn2_b64 vcc, exec, s[16:17]
	s_mov_b32 s18, s33
	s_nop 6
	v_cvt_pk_bf16_f32 v0, v0, v1
	v_cvt_pk_bf16_f32 v1, v2, v3
	global_store_dwordx2 v[80:81], v[0:1], off
	v_cvt_pk_bf16_f32 v0, v4, v5
	v_cvt_pk_bf16_f32 v1, v6, v7
	global_store_dwordx2 v[80:81], v[0:1], off offset:16
	v_cvt_pk_bf16_f32 v0, v8, v9
	v_cvt_pk_bf16_f32 v1, v10, v11
	global_store_dwordx2 v[80:81], v[0:1], off offset:32
	v_cvt_pk_bf16_f32 v0, v12, v13
	v_cvt_pk_bf16_f32 v1, v14, v15
	global_store_dwordx2 v[80:81], v[0:1], off offset:48
	s_cbranch_vccz .LBB0_242
.LBB0_240:
	s_add_i32 s33, s18, s28
	s_cmpk_gt_i32 s33, 0x5ff
	s_cselect_b64 s[16:17], -1, 0
	s_cmp_lg_u32 s1, 0
	s_cbranch_scc1 .Lr1a_skip1
	s_and_b64 vcc, exec, s[16:17]
	s_cbranch_vccnz .Lr1a_skip1
	s_mul_hi_i32 s34, s33, 0x2aaaaaab
	s_lshr_b32 s35, s34, 31
	s_add_i32 s40, s34, s35
	s_ashr_i32 s34, s40, 6
	s_ashr_i32 s35, s34, 31
	s_lshl_b32 s36, s40, 6
	s_lshl_b64 s[34:35], s[34:35], 12
	s_and_b32 s36, s36, 0xfc0
	s_or_b32 s34, s34, s36
	v_or_b32_e32 v2, s34, v16
	v_mov_b64_e32 v[0:1], s[12:13]
	s_mul_i32 s36, s40, 0xfffffd00
	v_mad_u64_u32 v[2:3], s[38:39], v2, s22, v[0:1]
	s_add_i32 s36, s25, s36
	s_mul_i32 s38, s40, 0xfffffe80
	s_ashr_i32 s37, s36, 31
	v_cndmask_b32_e64 v4, v75, v76, s[4:5]
	s_add_i32 s38, s38, s23
	s_andn2_b32 s19, 1, s1
	v_mad_i32_i24 v3, s35, v74, v3
	v_add3_u32 v18, s38, v20, v4
	s_lshl_b64 s[36:37], s[36:37], 1
	s_mul_i32 s19, s19, 0xc000
	v_lshl_add_u64 v[4:5], v[18:19], 1, v[2:3]
	v_lshl_add_u64 v[2:3], v[2:3], 0, s[36:37]
	s_add_i32 s19, s19, 0
	v_lshl_add_u64 v[2:3], v[20:21], 1, v[2:3]
	s_add_i32 s39, s19, s3
	s_mov_b32 s40, m0
	s_mov_b32 m0, s39
	s_nop 0
	global_load_lds_dwordx4 v[4:5], off
	s_mov_b32 m0, s40
	v_lshl_add_u64 v[2:3], v[2:3], 0, s[14:15]
	s_addk_i32 s39, 0x4000
	s_mov_b32 s40, m0
	s_mov_b32 m0, s39
	s_nop 0
	global_load_lds_dwordx4 v[2:3], off
	s_mov_b32 m0, s40
	v_cndmask_b32_e64 v2, v75, v76, s[10:11]
	v_add3_u32 v18, s38, v22, v2
	v_or_b32_e32 v2, s34, v24
	v_mad_u64_u32 v[0:1], s[38:39], v2, s22, v[0:1]
	v_mad_i32_i24 v1, s35, v74, v1
	v_lshl_add_u64 v[2:3], v[18:19], 1, v[0:1]
	v_lshl_add_u64 v[0:1], v[0:1], 0, s[36:37]
	s_add_i32 s19, s19, s7
	s_mov_b32 s34, m0
	s_mov_b32 m0, s19
	s_nop 0
	global_load_lds_dwordx4 v[2:3], off
	s_mov_b32 m0, s34
	v_lshl_add_u64 v[0:1], v[22:23], 1, v[0:1]
	v_lshl_add_u64 v[0:1], v[0:1], 0, s[14:15]
	s_addk_i32 s19, 0x4000
	s_mov_b32 s34, m0
	s_mov_b32 m0, s19
	s_nop 0
	global_load_lds_dwordx4 v[0:1], off
	s_mov_b32 m0, s34
.Lr1a_skip1:
	s_add_i32 s100, s33, s28
	s_cmpk_gt_i32 s100, 0x5ff
	s_cbranch_scc1 .Lr1a_skip2
	s_add_i32 s101, s98, 0x18000
	s_sub_i32 s19, s101, 0x24000
	s_cmp_lt_u32 s101, 0x24000
	s_cselect_b32 s101, s101, s19
	s_add_i32 s99, s23, s24
	s_mul_hi_i32 s34, s100, 0x2aaaaaab
	s_add_i32 s100, s25, s26
	s_lshr_b32 s35, s34, 31
	s_add_i32 s40, s34, s35
	s_ashr_i32 s34, s40, 6
	s_ashr_i32 s35, s34, 31
	s_lshl_b32 s36, s40, 6
	s_lshl_b64 s[34:35], s[34:35], 12
	s_and_b32 s36, s36, 0xfc0
	s_or_b32 s34, s34, s36
	v_or_b32_e32 v2, s34, v16
	v_mov_b64_e32 v[0:1], s[12:13]
	s_mul_i32 s36, s40, 0xfffffd00
	v_mad_u64_u32 v[2:3], s[38:39], v2, s22, v[0:1]
	s_add_i32 s36, s100, s36
	s_mul_i32 s38, s40, 0xfffffe80
	s_ashr_i32 s37, s36, 31
	v_cndmask_b32_e64 v4, v75, v76, s[4:5]
	s_add_i32 s38, s38, s99
	s_mov_b32 s19, s101
	v_mad_i32_i24 v3, s35, v74, v3
	v_add3_u32 v18, s38, v20, v4
	s_lshl_b64 s[36:37], s[36:37], 1
	s_nop 0
	v_lshl_add_u64 v[4:5], v[18:19], 1, v[2:3]
	v_lshl_add_u64 v[2:3], v[2:3], 0, s[36:37]
	s_add_i32 s19, s19, 0
	v_lshl_add_u64 v[2:3], v[20:21], 1, v[2:3]
	s_add_i32 s39, s19, s3
	s_mov_b32 s40, m0
	s_mov_b32 m0, s39
	s_nop 0
	global_load_lds_dwordx4 v[4:5], off
	s_mov_b32 m0, s40
	v_lshl_add_u64 v[2:3], v[2:3], 0, s[14:15]
	s_addk_i32 s39, 0x4000
	s_mov_b32 s40, m0
	s_mov_b32 m0, s39
	s_nop 0
	global_load_lds_dwordx4 v[2:3], off
	s_mov_b32 m0, s40
	v_cndmask_b32_e64 v2, v75, v76, s[10:11]
	v_add3_u32 v18, s38, v22, v2
	v_or_b32_e32 v2, s34, v24
	v_mad_u64_u32 v[0:1], s[38:39], v2, s22, v[0:1]
	v_mad_i32_i24 v1, s35, v74, v1
	v_lshl_add_u64 v[2:3], v[18:19], 1, v[0:1]
	v_lshl_add_u64 v[0:1], v[0:1], 0, s[36:37]
	s_add_i32 s19, s19, s7
	s_mov_b32 s34, m0
	s_mov_b32 m0, s19
	s_nop 0
	global_load_lds_dwordx4 v[2:3], off
	s_mov_b32 m0, s34
	v_lshl_add_u64 v[0:1], v[22:23], 1, v[0:1]
	v_lshl_add_u64 v[0:1], v[0:1], 0, s[14:15]
	s_addk_i32 s19, 0x4000
	s_mov_b32 s34, m0
	s_mov_b32 m0, s19
	s_nop 0
	global_load_lds_dwordx4 v[0:1], off
	s_mov_b32 m0, s34
.Lr1a_skip2:
	s_branch .LBB0_239

; __device__ __forceinline__ s16x4 vtr(ldsp p) { typedef short v4i16_t __attribute__((ext_vector_type(4))); return __builtin_bit_cast(s16x4, __builtin_amdgcn_ds_read_tr16_b64_v4i16((ALDS v4i16_t*)p)); }
; __device__ __forceinline__ void wait_all_barrier() { asm volatile("s_waitcnt vmcnt(0) lgkmcnt(0)\n\ts_barrier" ::: "memory"); }
; __device__ __forceinline__ bf16x8 tr_nat(unsigned img, int c, int ks, int lane) {
;     const unsigned hh = lane >> 5, blk = (lane >> 4) & 1, qq = (lane & 15) >> 2, p = lane & 3;
;     const unsigned row0 = 16u * ks + 8u * hh + qq, ch = 4u * c + 2u * blk + (p >> 1);
;     const s16x4 lo = vtr((ldsp)(size_t)(img + off_b(row0, ch) + 8u * (p & 1u))), hi = vtr((ldsp)(size_t)(img + off_b(row0 + 4u, ch) + 8u * (p & 1u)));
; __device__ __forceinline__ void r1_phase(ldsp lds, const bf16* U, bf16* KV, int G, int bx, int wave, int lane) {
;     const unsigned lds0 = (unsigned)(size_t)lds;
;     const int dt = wave & 1, et = wave >> 1, r = lane & 31, hh = lane >> 5;
;     if (bx < N_ITEMS) stage_item<false>(lds, 0, bx, U, nullptr, wave, lane);
;     wait_all_barrier();
;     int k = 0;
;     for (int item = bx; item < N_ITEMS; item += G, ++k) {
;         const unsigned st = lds0 + (k & 1) * STAGE;
;         if (item + G < N_ITEMS) stage_item<false>(lds, ((k + 1) & 1) * STAGE, item + G, U, nullptr, wave, lane);
;         int b, n, h; decode(item, b, n, h);
;         const float lg2 = log2f(1.0f - exp2f(-5.0f - (float)h));
;         f32x16 acc;
; #pragma unroll
;         for (int i = 0; i < 16; ++i) acc[i] = 0.f;
; #pragma unroll
;         for (int ks = 0; ks < 4; ++ks) {
;             const bf16x8 kf = tr_nat(st, dt, ks, lane), vf = tr_nat(st + 16384, et, ks, lane);
;             float kd[8];
; #pragma unroll
;             for (int jj = 0; jj < 8; ++jj) kd[jj] = bfs(kf[jj]) * __builtin_amdgcn_exp2f(lg2 * (float)(63 - (16 * ks + 8 * hh + jj)));
.LBB0_1305:
	s_waitcnt vmcnt(0) lgkmcnt(0)
	s_barrier
	s_and_b64 vcc, exec, s[8:9]
	s_cbranch_vccnz .LBB0_1310
	v_readlane_b32 s3, v252, 1
	s_lshl_b32 s4, s3, 1
	v_lshrrev_b32_e32 v4, 4, v0
	s_and_b32 s0, s4, 2
	s_or_b32 s4, s4, 1
	v_and_b32_e32 v2, 15, v1
	v_lshlrev_b32_e32 v3, 2, v4
	s_and_b32 s5, s4, 3
	v_bitop3_b32 v5, v3, v2, s0 bitop3:0x36
	v_bitop3_b32 v2, v3, v2, s5 bitop3:0x36
	v_cmp_gt_u32_e64 s[16:17], 8, v2
	v_lshlrev_b32_e32 v22, 3, v2
	v_lshrrev_b32_e32 v2, 3, v1
	v_cmp_gt_u32_e64 s[14:15], 8, v5
	v_lshlrev_b32_e32 v20, 3, v5
	v_lshl_or_b32 v24, s4, 2, v4
	s_lshl_b32 s12, s4, 10
	v_lshrrev_b32_e32 v5, 2, v0
	v_and_b32_e32 v2, 2, v2
	v_readlane_b32 s4, v252, 14
	v_and_b32_e32 v6, 11, v5
	v_lshl_or_b32 v7, s6, 2, v2
	v_bfe_u32 v8, v1, 1, 1
	v_lshl_or_b32 v10, s4, 2, v2
	v_or_b32_e32 v3, v7, v8
	v_and_b32_e32 v1, 12, v1
	v_lshrrev_b32_e32 v9, 2, v6
	v_or_b32_e32 v2, v10, v8
	v_bitop3_b32 v3, v9, v3, v1 bitop3:0x36
	v_bitop3_b32 v2, v9, v2, v1 bitop3:0x36
	v_or3_b32 v1, v1, v4, 1
	v_or_b32_e32 v16, s41, v4
	v_bitop3_b32 v4, v7, v1, v8 bitop3:0x36
	v_bitop3_b32 v7, v5, 63, 8 bitop3:0x6c
	v_cvt_f32_ubyte0_e32 v33, v7
	v_bitop3_b32 v7, v5, 62, 8 bitop3:0x6c
	v_cvt_f32_ubyte0_e32 v34, v7
	v_bitop3_b32 v7, v5, 61, 8 bitop3:0x6c
	v_cvt_f32_ubyte0_e32 v35, v7
	v_bitop3_b32 v7, v5, 60, 8 bitop3:0x6c
	v_cvt_f32_ubyte0_e32 v36, v7
	v_bitop3_b32 v7, v5, 59, 8 bitop3:0x6c
	v_cvt_f32_ubyte0_e32 v37, v7
	v_bitop3_b32 v7, v5, 58, 8 bitop3:0x6c
	v_cvt_f32_ubyte0_e32 v38, v7
	v_bitop3_b32 v7, v5, 57, 8 bitop3:0x6c
	v_lshlrev_b32_e32 v30, 8, v6
	v_lshlrev_b32_e32 v6, 8, v5
	v_bitop3_b32 v1, v10, v1, v8 bitop3:0x36
	v_cvt_f32_ubyte0_e32 v39, v7
	v_bitop3_b32 v7, v5, 56, 8 bitop3:0x6c
	v_lshlrev_b32_e32 v4, 4, v4
	v_lshlrev_b32_e32 v1, 4, v1
	v_cvt_f32_ubyte0_e32 v40, v7
	v_or_b32_e32 v7, 0x1400, v6
	v_or_b32_e32 v42, v4, v7
	v_or_b32_e32 v43, v1, v7
	v_bitop3_b32 v7, v5, 47, 8 bitop3:0x6c
	v_cvt_f32_ubyte0_e32 v44, v7
	v_bitop3_b32 v7, v5, 46, 8 bitop3:0x6c
	v_cvt_f32_ubyte0_e32 v45, v7
	v_bitop3_b32 v7, v5, 45, 8 bitop3:0x6c
	v_cvt_f32_ubyte0_e32 v46, v7
	v_bitop3_b32 v7, v5, 44, 8 bitop3:0x6c
	v_cvt_f32_ubyte0_e32 v47, v7
	v_bitop3_b32 v7, v5, 43, 8 bitop3:0x6c
	v_cvt_f32_ubyte0_e32 v48, v7
	v_bitop3_b32 v7, v5, 42, 8 bitop3:0x6c
	v_cvt_f32_ubyte0_e32 v49, v7
	v_bitop3_b32 v7, v5, 41, 8 bitop3:0x6c
	v_cvt_f32_ubyte0_e32 v50, v7
	v_bitop3_b32 v7, v5, 40, 8 bitop3:0x6c
	v_or_b32_e32 v9, 0x400, v6
	v_cvt_f32_ubyte0_e32 v51, v7
	v_or_b32_e32 v7, 0x2400, v6
	v_or_b32_e32 v6, 0x3400, v6
	v_or_b32_e32 v32, v1, v9
	v_or_b32_e32 v54, v1, v7
	v_or_b32_e32 v65, v1, v6
	v_bitop3_b32 v1, v5, 15, 8 bitop3:0x6c
	v_or_b32_e32 v53, v4, v7
	v_bitop3_b32 v7, v5, 31, 8 bitop3:0x6c
	v_cvt_f32_ubyte0_e32 v66, v1
	v_bitop3_b32 v1, v5, 14, 8 bitop3:0x6c
	v_cvt_f32_ubyte0_e32 v55, v7
	v_bitop3_b32 v7, v5, 30, 8 bitop3:0x6c
	v_cvt_f32_ubyte0_e32 v67, v1
	v_bitop3_b32 v1, v5, 13, 8 bitop3:0x6c
	v_cvt_f32_ubyte0_e32 v56, v7
	v_bitop3_b32 v7, v5, 29, 8 bitop3:0x6c
	v_cvt_f32_ubyte0_e32 v68, v1
	v_bitop3_b32 v1, v5, 12, 8 bitop3:0x6c
	s_lshl_b32 s3, s3, 11
	s_lshl_b32 s4, s4, 6
	v_cvt_f32_ubyte0_e32 v57, v7
	v_bitop3_b32 v7, v5, 28, 8 bitop3:0x6c
	v_cvt_f32_ubyte0_e32 v69, v1
	v_bitop3_b32 v1, v5, 11, 8 bitop3:0x6c
	v_lshlrev_b32_e32 v17, 4, v3
	v_lshlrev_b32_e32 v3, 3, v0
	s_add_u32 s20, s20, s4
	v_cvt_f32_ubyte0_e32 v58, v7
	v_bitop3_b32 v7, v5, 27, 8 bitop3:0x6c
	v_cvt_f32_ubyte0_e32 v70, v1
	v_bitop3_b32 v1, v5, 10, 8 bitop3:0x6c
	v_lshlrev_b32_e32 v0, 8, v0
	v_mov_b32_e32 v19, 0
	s_addc_u32 s21, s21, 0
	v_and_b32_e32 v18, 8, v5
	v_cvt_f32_ubyte0_e32 v59, v7
	v_bitop3_b32 v7, v5, 26, 8 bitop3:0x6c
	v_cvt_f32_ubyte0_e32 v71, v1
	v_bitop3_b32 v1, v5, 9, 8 bitop3:0x6c
	v_and_b32_e32 v0, 0x1f00, v0
	v_and_b32_e32 v25, 8, v3
	v_lshlrev_b32_e32 v28, 4, v2
	v_lshl_add_u64 v[2:3], s[20:21], 0, v[18:19]
	v_cvt_f32_ubyte0_e32 v60, v7
	v_bitop3_b32 v7, v5, 25, 8 bitop3:0x6c
	v_cvt_f32_ubyte0_e32 v72, v1
	v_bitop3_b32 v1, v5, 8, v5 bitop3:0xc
	v_lshl_or_b32 v18, s6, 13, v0
	v_cvt_f32_ubyte0_e32 v61, v7
	v_bitop3_b32 v7, v5, 24, 8 bitop3:0x6c
	v_cvt_f32_ubyte0_e32 v73, v1
	v_lshl_add_u64 v[0:1], v[2:3], 0, v[18:19]
	s_mov_b64 s[20:21], 0xfa00000
	s_add_i32 s4, s28, s2
	s_mov_b32 s0, 0
	v_mov_b32_e32 v21, v19
	v_mov_b32_e32 v23, v19
	v_or_b32_e32 v29, 0x4000, v25
	v_or_b32_e32 v31, v4, v9
	v_or_b32_e32 v41, 0x1000, v30
	s_movk_i32 s13, 0x1400
	v_or_b32_e32 v52, 0x2000, v30
	v_cvt_f32_ubyte0_e32 v62, v7
	v_or_b32_e32 v63, 0x3000, v30
	v_or_b32_e32 v64, v4, v6
	v_lshl_add_u64 v[26:27], v[0:1], 0, s[20:21]
	s_lshl_b32 s26, s4, 6
	s_lshl_b32 s27, s28, 6
	s_lshl_b32 s33, s4, 7
	s_lshl_b32 s40, s28, 7
	s_mov_b64 s[20:21], 0x600
	s_add_i32 s42, 0, 0xc000
	s_mov_b32 s43, 0xc2fc0000
	s_mov_b32 s44, 0x800000
	v_mov_b32_e32 v74, 0x1400
	v_not_b32_e32 v75, 63
	v_mov_b32_e32 v76, 0x180
	v_mov_b32_e32 v77, 0x42800000
	v_mov_b32_e32 v78, 0x42000000
	s_mov_b32 s24, s2
	s_mov_b32 s98, 0
	s_branch .LBB0_1308
; __device__ __forceinline__ unsigned cvtpk(float lo, float hi) { f32x2_t v = {lo, hi}; bf16x2_t b = __builtin_convertvector(v, bf16x2_t); return __builtin_bit_cast(unsigned, b); }
; __device__ __forceinline__ void wait_all_barrier() { asm volatile("s_waitcnt vmcnt(0) lgkmcnt(0)\n\ts_barrier" ::: "memory"); }
; __device__ __forceinline__ void r1_phase(ldsp lds, const bf16* U, bf16* KV, int G, int bx, int wave, int lane) {
;     ...
;         int b, n, h; decode(item, b, n, h);
;         const float lg2 = log2f(1.0f - exp2f(-5.0f - (float)h));
;         f32x16 acc;
; #pragma unroll
;         for (int i = 0; i < 16; ++i) acc[i] = 0.f;
; #pragma unroll
;         for (int ks = 0; ks < 4; ++ks) {
;             const bf16x8 kf = tr_nat(st, dt, ks, lane), vf = tr_nat(st + 16384, et, ks, lane);
;             float kd[8];
; #pragma unroll
;             for (int jj = 0; jj < 8; ++jj) kd[jj] = bfs(kf[jj]) * __builtin_amdgcn_exp2f(lg2 * (float)(63 - (16 * ks + 8 * hh + jj)));
;             typedef unsigned u4 __attribute__((ext_vector_type(4)));
;             u4 w; w.x = cvtpk(kd[0], kd[1]); w.y = cvtpk(kd[2], kd[3]); w.z = cvtpk(kd[4], kd[5]); w.w = cvtpk(kd[6], kd[7]);
;             acc = __builtin_amdgcn_mfma_f32_32x32x16_bf16(vf, __builtin_bit_cast(bf16x8, w), acc, 0, 0, 0);
;         }
;         wait_all_barrier();
.LBB0_1307:
	s_nop 0
	s_mul_hi_i32 s5, s24, 0x2aaaaaab
	s_mov_b32 s4, s98
	s_lshr_b32 s25, s5, 31
	s_add_i32 s5, s5, s25
	s_mul_i32 s5, s5, 6
	s_sub_i32 s5, s24, s5
	v_cvt_f32_i32_e32 v0, s5
	v_or_b32_e32 v18, s4, v25
	v_add_u32_e32 v96, v18, v17
	v_add_u32_e32 v79, s4, v29
	v_sub_f32_e32 v0, 0xc0a00000, v0
	v_cmp_gt_f32_e32 vcc, s43, v0
	s_and_b64 s[46:47], vcc, exec
	s_cselect_b32 s5, 0xffffffc0, 0
	v_cndmask_b32_e32 v1, 0, v77, vcc
	v_add_f32_e32 v0, v0, v1
	v_exp_f32_e32 v0, v0
	v_add_u32_e32 v80, v96, v41
	v_add_u32_e32 v98, v79, v28
	ds_read_b64_tr_b16 v[84:85], v80
	v_ldexp_f32 v0, v0, s5
	v_sub_f32_e32 v0, 1.0, v0
	v_cmp_gt_f32_e32 vcc, s44, v0
	s_and_b64 s[46:47], vcc, exec
	s_cselect_b32 s5, 32, 0
	v_ldexp_f32 v0, v0, s5
	v_log_f32_e32 v0, v0
	v_cndmask_b32_e32 v1, 0, v78, vcc
	v_add_u32_e32 v2, v32, v79
	ds_read_b64_tr_b16 v[2:3], v2
	v_sub_f32_e32 v97, v0, v1
	v_add_u32_e32 v0, v96, v30
	ds_read_b64_tr_b16 v[4:5], v0
	v_add_u32_e32 v0, v31, v18
	v_mul_f32_e32 v8, v97, v33
	v_mul_f32_e32 v9, v97, v34
	ds_read_b64_tr_b16 v[6:7], v0
	s_waitcnt lgkmcnt(1)
	v_and_b32_e32 v11, 0xffff0000, v4
	v_lshlrev_b32_e32 v10, 16, v4
	v_mul_f32_e32 v4, v97, v35
	v_exp_f32_e32 v8, v8
	v_exp_f32_e32 v9, v9
	v_exp_f32_e32 v12, v4
	v_mul_f32_e32 v4, v97, v36
	v_exp_f32_e32 v13, v4
	v_add_u32_e32 v0, v98, v30
	ds_read_b64_tr_b16 v[0:1], v0
	v_pk_mul_f32 v[8:9], v[8:9], v[10:11]
	v_and_b32_e32 v11, 0xffff0000, v5
	v_lshlrev_b32_e32 v10, 16, v5
	v_pk_mul_f32 v[10:11], v[12:13], v[10:11]
	v_mul_f32_e32 v4, v97, v37
	v_mul_f32_e32 v5, v97, v38
	s_waitcnt lgkmcnt(1)
	v_and_b32_e32 v13, 0xffff0000, v6
	v_lshlrev_b32_e32 v12, 16, v6
	v_mul_f32_e32 v6, v97, v39
	v_exp_f32_e32 v4, v4
	v_exp_f32_e32 v5, v5
	v_exp_f32_e32 v14, v6
	v_mul_f32_e32 v6, v97, v40
	v_exp_f32_e32 v15, v6
	v_add_u32_e32 v80, v42, v18
	v_mul_f32_e32 v88, v97, v44
	v_mul_f32_e32 v89, v97, v45
	v_and_b32_e32 v91, 0xffff0000, v84
	v_lshlrev_b32_e32 v90, 16, v84
	v_mul_f32_e32 v84, v97, v46
	ds_read_b64_tr_b16 v[86:87], v80
	v_exp_f32_e32 v88, v88
	v_exp_f32_e32 v89, v89
	v_exp_f32_e32 v92, v84
	v_mul_f32_e32 v84, v97, v47
	v_exp_f32_e32 v93, v84
	v_pk_mul_f32 v[12:13], v[4:5], v[12:13]
	v_and_b32_e32 v5, 0xffff0000, v7
	v_lshlrev_b32_e32 v4, 16, v7
	v_pk_mul_f32 v[14:15], v[14:15], v[4:5]
	v_add_u32_e32 v80, v98, v41
	v_add_u32_e32 v82, v43, v79
	v_cvt_pk_bf16_f32 v4, v8, v9
	v_cvt_pk_bf16_f32 v5, v10, v11
	v_cvt_pk_bf16_f32 v6, v12, v13
	v_cvt_pk_bf16_f32 v7, v14, v15
	ds_read_b64_tr_b16 v[80:81], v80
	ds_read_b64_tr_b16 v[82:83], v82
	v_pk_mul_f32 v[88:89], v[88:89], v[90:91]
	v_and_b32_e32 v91, 0xffff0000, v85
	v_lshlrev_b32_e32 v90, 16, v85
	s_waitcnt lgkmcnt(3)
	v_mfma_f32_32x32x16_bf16 v[0:15], v[0:3], v[4:7], 0
	v_mul_f32_e64 v90, v92, v90
	v_mul_f32_e64 v91, v93, v91
	v_mul_f32_e32 v84, v97, v48
	v_mul_f32_e32 v85, v97, v49
	s_waitcnt lgkmcnt(2)
	v_and_b32_e32 v93, 0xffff0000, v86
	v_lshlrev_b32_e32 v92, 16, v86
	v_mul_f32_e32 v86, v97, v50
	v_exp_f32_e32 v84, v84
	v_exp_f32_e32 v85, v85
	v_exp_f32_e32 v94, v86
	v_mul_f32_e32 v86, v97, v51
	v_exp_f32_e32 v95, v86
	v_pk_mul_f32 v[92:93], v[84:85], v[92:93]
	v_and_b32_e32 v85, 0xffff0000, v87
	v_lshlrev_b32_e32 v84, 16, v87
	v_pk_mul_f32 v[94:95], v[94:95], v[84:85]
	v_cvt_pk_bf16_f32 v84, v88, v89
	v_cvt_pk_bf16_f32 v85, v90, v91
	v_cvt_pk_bf16_f32 v86, v92, v93
	v_cvt_pk_bf16_f32 v87, v94, v95
	v_mul_f32_e32 v88, v97, v55
	v_mul_f32_e32 v89, v97, v56
	s_waitcnt lgkmcnt(0)
	v_mfma_f32_32x32x16_bf16 v[0:15], v[80:83], v[84:87], v[0:15]
	v_add_u32_e32 v80, v96, v52
	ds_read_b64_tr_b16 v[84:85], v80
	v_add_u32_e32 v80, v53, v18
	ds_read_b64_tr_b16 v[86:87], v80
	v_exp_f32_e32 v88, v88
	v_exp_f32_e32 v89, v89
	s_waitcnt lgkmcnt(1)
	v_and_b32_e32 v91, 0xffff0000, v84
	v_lshlrev_b32_e32 v90, 16, v84
	v_mul_f32_e32 v84, v97, v57
	v_exp_f32_e32 v92, v84
	v_mul_f32_e32 v84, v97, v58
	v_exp_f32_e32 v93, v84
	v_add_u32_e32 v80, v98, v52
	v_add_u32_e32 v82, v54, v79
	ds_read_b64_tr_b16 v[80:81], v80
	ds_read_b64_tr_b16 v[82:83], v82
	v_pk_mul_f32 v[88:89], v[88:89], v[90:91]
	v_and_b32_e32 v91, 0xffff0000, v85
	v_lshlrev_b32_e32 v90, 16, v85
	v_pk_mul_f32 v[90:91], v[92:93], v[90:91]
	v_mul_f32_e32 v84, v97, v59
	v_mul_f32_e32 v85, v97, v60
	s_waitcnt lgkmcnt(2)
	v_and_b32_e32 v93, 0xffff0000, v86
	v_lshlrev_b32_e32 v92, 16, v86
	v_mul_f32_e32 v86, v97, v61
	v_exp_f32_e32 v84, v84
	v_exp_f32_e32 v85, v85
	v_exp_f32_e32 v94, v86
	v_mul_f32_e32 v86, v97, v62
	v_exp_f32_e32 v95, v86
	v_pk_mul_f32 v[92:93], v[84:85], v[92:93]
	v_and_b32_e32 v85, 0xffff0000, v87
	v_lshlrev_b32_e32 v84, 16, v87
	v_pk_mul_f32 v[94:95], v[94:95], v[84:85]
	v_cvt_pk_bf16_f32 v84, v88, v89
	v_cvt_pk_bf16_f32 v85, v90, v91
	v_cvt_pk_bf16_f32 v86, v92, v93
	v_cvt_pk_bf16_f32 v87, v94, v95
	v_add_u32_e32 v18, v64, v18
	s_ashr_i32 s25, s24, 31
	s_waitcnt lgkmcnt(0)
	v_mfma_f32_32x32x16_bf16 v[0:15], v[80:83], v[84:87], v[0:15]
	v_add_u32_e32 v80, v96, v63
	ds_read_b64_tr_b16 v[86:87], v18
	v_add_u32_e32 v18, v98, v63
	ds_read_b64_tr_b16 v[84:85], v80
	ds_read_b64_tr_b16 v[80:81], v18
	v_add_u32_e32 v18, v65, v79
	ds_read_b64_tr_b16 v[82:83], v18
	v_mul_f32_e32 v18, v97, v66
	v_exp_f32_e32 v88, v18
	v_mul_f32_e32 v18, v97, v67
	v_exp_f32_e32 v89, v18
	v_mul_f32_e32 v18, v97, v68
	v_exp_f32_e32 v92, v18
	v_mul_f32_e32 v18, v97, v69
	v_exp_f32_e32 v93, v18
	v_mul_f32_e32 v18, v97, v70
	s_waitcnt lgkmcnt(2)
	v_and_b32_e32 v91, 0xffff0000, v84
	v_lshlrev_b32_e32 v90, 16, v84
	v_exp_f32_e32 v84, v18
	v_mul_f32_e32 v18, v97, v71
	v_pk_mul_f32 v[88:89], v[88:89], v[90:91]
	v_and_b32_e32 v91, 0xffff0000, v85
	v_lshlrev_b32_e32 v90, 16, v85
	v_exp_f32_e32 v85, v18
	v_mul_f32_e32 v18, v97, v72
	v_exp_f32_e32 v94, v18
	v_mul_f32_e32 v18, v97, v73
	v_exp_f32_e32 v95, v18
	v_pk_mul_f32 v[90:91], v[92:93], v[90:91]
	v_and_b32_e32 v93, 0xffff0000, v86
	v_lshlrev_b32_e32 v92, 16, v86
	v_pk_mul_f32 v[92:93], v[84:85], v[92:93]
	v_and_b32_e32 v85, 0xffff0000, v87
	v_lshlrev_b32_e32 v84, 16, v87
	v_pk_mul_f32 v[94:95], v[94:95], v[84:85]
	v_cvt_pk_bf16_f32 v84, v88, v89
	v_cvt_pk_bf16_f32 v85, v90, v91
	v_cvt_pk_bf16_f32 v86, v92, v93
	v_cvt_pk_bf16_f32 v87, v94, v95
	s_lshl_b64 s[24:25], s[24:25], 14
	s_add_i32 s5, s45, s28
	s_cmpk_gt_i32 s5, 0x5ff
	s_cbranch_scc1 .Lr1b_w0
	s_waitcnt vmcnt(4) lgkmcnt(0)
	s_branch .Lr1b_wb

; template <bool WITH_PREV>
; __device__ __forceinline__ void stage_item(ldsp lds, int stage, int item, const bf16* U, const bf16* PREV, int wave, int lane) {
;     int b, n, h; decode(item, b, n, h);
;     const int prow = lane >> 4, chp = lane & 15;
; #pragma unroll
;     for (int i = 0; i < 2; ++i) { const int pi = wave * 2 + i, row = 4 * pi + prow; const unsigned ch = (unsigned)chp ^ (((unsigned)prow << 2) | ((unsigned)pi & 3u));
;         const bf16* urow = U + ((size_t)b * SEQ + 64 * n + row) * INW;
;         dma16(urow + (ch < 8u ? 384 + h * 64 + ch * 8 : h * 64 + (ch - 8u) * 8), lds + stage + 1024 * pi);
;         dma16(urow + 768 + h * 128 + ch * 8, lds + stage + 16384 + 1024 * pi);
;         if (WITH_PREV) dma16(PREV + ((size_t)item * 64 + row) * 128 + ch * 8, lds + stage + 32768 + 1024 * pi); }
; __device__ __forceinline__ void r1_phase(ldsp lds, const bf16* U, bf16* KV, int G, int bx, int wave, int lane) {
;     ...
;     for (int item = bx; item < N_ITEMS; item += G, ++k) {
;         const unsigned st = lds0 + (k & 1) * STAGE;
;         if (item + G < N_ITEMS) stage_item<false>(lds, ((k + 1) & 1) * STAGE, item + G, U, nullptr, wave, lane);
;         int b, n, h; decode(item, b, n, h);
;         const float lg2 = log2f(1.0f - exp2f(-5.0f - (float)h));
;         f32x16 acc;
; #pragma unroll
;         for (int i = 0; i < 16; ++i) acc[i] = 0.f;
; #pragma unroll
;         for (int ks = 0; ks < 4; ++ks) {
;             const bf16x8 kf = tr_nat(st, dt, ks, lane), vf = tr_nat(st + 16384, et, ks, lane);
;             float kd[8];
; #pragma unroll
;             for (int jj = 0; jj < 8; ++jj) kd[jj] = bfs(kf[jj]) * __builtin_amdgcn_exp2f(lg2 * (float)(63 - (16 * ks + 8 * hh + jj)));
;             typedef unsigned u4 __attribute__((ext_vector_type(4)));
;             u4 w; w.x = cvtpk(kd[0], kd[1]); w.y = cvtpk(kd[2], kd[3]); w.z = cvtpk(kd[4], kd[5]); w.w = cvtpk(kd[6], kd[7]);
;             acc = __builtin_amdgcn_mfma_f32_32x32x16_bf16(vf, __builtin_bit_cast(bf16x8, w), acc, 0, 0, 0);
;         }
;         wait_all_barrier();
;         bf16* kvp = KV + ((size_t)item * 64 + 32 * dt + r) * 128 + 32 * et + 4 * hh;
; #pragma unroll
;         for (int g4 = 0; g4 < 4; ++g4) { v2u pk; pk.x = cvtpk(acc[4 * g4], acc[4 * g4 + 1]); pk.y = cvtpk(acc[4 * g4 + 2], acc[4 * g4 + 3]); *(v2u*)(kvp + 8 * g4) = pk; }
;     }
.Lr1b_wb:
	s_barrier
	s_add_i32 s0, s0, 1
	s_add_i32 s98, s98, 0xc000
	s_cmp_eq_u32 s98, 0x24000
	s_cselect_b32 s98, 0, s98
	s_waitcnt lgkmcnt(0)
	v_mfma_f32_32x32x16_bf16 v[0:15], v[80:83], v[84:87], v[0:15]
	v_lshl_add_u64 v[80:81], v[26:27], 0, s[24:25]
	s_add_i32 s26, s26, s27
	s_add_i32 s33, s33, s40
	s_andn2_b64 vcc, exec, s[22:23]
	s_mov_b32 s24, s45
	s_nop 6
	v_cvt_pk_bf16_f32 v0, v0, v1
	v_cvt_pk_bf16_f32 v1, v2, v3
	global_store_dwordx2 v[80:81], v[0:1], off
	v_cvt_pk_bf16_f32 v0, v4, v5
	v_cvt_pk_bf16_f32 v1, v6, v7
	global_store_dwordx2 v[80:81], v[0:1], off offset:16
	v_cvt_pk_bf16_f32 v0, v8, v9
	v_cvt_pk_bf16_f32 v1, v10, v11
	global_store_dwordx2 v[80:81], v[0:1], off offset:32
	v_cvt_pk_bf16_f32 v0, v12, v13
	v_cvt_pk_bf16_f32 v1, v14, v15
	global_store_dwordx2 v[80:81], v[0:1], off offset:48
	s_cbranch_vccz .LBB0_1310
.LBB0_1308:
	s_add_i32 s45, s24, s28
	s_cmpk_gt_i32 s45, 0x5ff
	s_cselect_b64 s[22:23], -1, 0
	s_cmp_lg_u32 s0, 0
	s_cbranch_scc1 .Lr1b_skip1
	s_and_b64 vcc, exec, s[22:23]
	s_cbranch_vccnz .Lr1b_skip1
	s_mul_hi_i32 s5, s45, 0x2aaaaaab
	s_lshr_b32 s25, s5, 31
	s_add_i32 s5, s5, s25
	s_ashr_i32 s46, s5, 6
	s_ashr_i32 s47, s46, 31
	s_lshl_b32 s25, s5, 6
	s_lshl_b64 s[46:47], s[46:47], 12
	s_and_b32 s25, s25, 0xfc0
	s_or_b32 s25, s46, s25
	s_mul_i32 s46, s5, 0xfffffd00
	s_add_i32 s48, s33, s46
	v_or_b32_e32 v2, s25, v16
	v_mov_b64_e32 v[0:1], s[18:19]
	s_mulk_i32 s5, 0xfe80
	s_ashr_i32 s49, s48, 31
	v_mad_u64_u32 v[2:3], s[50:51], v2, s13, v[0:1]
	v_cndmask_b32_e64 v4, v75, v76, s[14:15]
	s_add_i32 s5, s5, s26
	s_andn2_b32 s4, 1, s0
	v_mad_i32_i24 v3, s47, v74, v3
	v_add3_u32 v18, s5, v20, v4
	s_lshl_b64 s[48:49], s[48:49], 1
	s_mul_i32 s4, s4, 0xc000
	v_lshl_add_u64 v[4:5], v[18:19], 1, v[2:3]
	v_lshl_add_u64 v[2:3], v[2:3], 0, s[48:49]
	s_add_i32 s4, s4, 0
	v_lshl_add_u64 v[2:3], v[20:21], 1, v[2:3]
	s_add_i32 s46, s4, s3
	s_mov_b32 s50, m0
	s_mov_b32 m0, s46
	s_nop 0
	global_load_lds_dwordx4 v[4:5], off
	s_mov_b32 m0, s50
	v_lshl_add_u64 v[2:3], v[2:3], 0, s[20:21]
	s_addk_i32 s46, 0x4000
	s_mov_b32 s50, m0
	s_mov_b32 m0, s46
	s_nop 0
	global_load_lds_dwordx4 v[2:3], off
	s_mov_b32 m0, s50
	v_cndmask_b32_e64 v2, v75, v76, s[16:17]
	v_add3_u32 v18, s5, v22, v2
	v_or_b32_e32 v2, s25, v24
	v_mad_u64_u32 v[0:1], s[50:51], v2, s13, v[0:1]
	v_mad_i32_i24 v1, s47, v74, v1
	v_lshl_add_u64 v[2:3], v[18:19], 1, v[0:1]
	v_lshl_add_u64 v[0:1], v[0:1], 0, s[48:49]
	s_add_i32 s4, s4, s12
	s_mov_b32 s5, m0
	s_mov_b32 m0, s4
	s_nop 0
	global_load_lds_dwordx4 v[2:3], off
	s_mov_b32 m0, s5
	v_lshl_add_u64 v[0:1], v[22:23], 1, v[0:1]
	v_lshl_add_u64 v[0:1], v[0:1], 0, s[20:21]
	s_addk_i32 s4, 0x4000
	s_mov_b32 s5, m0
	s_mov_b32 m0, s4
	s_nop 0
	global_load_lds_dwordx4 v[0:1], off
	s_mov_b32 m0, s5
.Lr1b_skip1:
	s_add_i32 s100, s45, s28
	s_cmpk_gt_i32 s100, 0x5ff
	s_cbranch_scc1 .Lr1b_skip2
	s_add_i32 s101, s98, 0x18000
	s_sub_i32 s4, s101, 0x24000
	s_cmp_lt_u32 s101, 0x24000
	s_cselect_b32 s101, s101, s4
	s_add_i32 s99, s26, s27
	s_mul_hi_i32 s5, s100, 0x2aaaaaab
	s_add_i32 s100, s33, s40
	s_lshr_b32 s25, s5, 31
	s_add_i32 s5, s5, s25
	s_ashr_i32 s46, s5, 6
	s_ashr_i32 s47, s46, 31
	s_lshl_b32 s25, s5, 6
	s_lshl_b64 s[46:47], s[46:47], 12
	s_and_b32 s25, s25, 0xfc0
	s_or_b32 s25, s46, s25
	s_mul_i32 s46, s5, 0xfffffd00
	s_add_i32 s48, s100, s46
	v_or_b32_e32 v2, s25, v16
	v_mov_b64_e32 v[0:1], s[18:19]
	s_mulk_i32 s5, 0xfe80
	s_ashr_i32 s49, s48, 31
	v_mad_u64_u32 v[2:3], s[50:51], v2, s13, v[0:1]
	v_cndmask_b32_e64 v4, v75, v76, s[14:15]
	s_add_i32 s5, s5, s99
	s_mov_b32 s4, s101
	v_mad_i32_i24 v3, s47, v74, v3
	v_add3_u32 v18, s5, v20, v4
	s_lshl_b64 s[48:49], s[48:49], 1
	s_nop 0
	v_lshl_add_u64 v[4:5], v[18:19], 1, v[2:3]
	v_lshl_add_u64 v[2:3], v[2:3], 0, s[48:49]
	s_add_i32 s4, s4, 0
	v_lshl_add_u64 v[2:3], v[20:21], 1, v[2:3]
	s_add_i32 s46, s4, s3
	s_mov_b32 s50, m0
	s_mov_b32 m0, s46
	s_nop 0
	global_load_lds_dwordx4 v[4:5], off
	s_mov_b32 m0, s50
	v_lshl_add_u64 v[2:3], v[2:3], 0, s[20:21]
	s_addk_i32 s46, 0x4000
	s_mov_b32 s50, m0
	s_mov_b32 m0, s46
	s_nop 0
	global_load_lds_dwordx4 v[2:3], off
	s_mov_b32 m0, s50
	v_cndmask_b32_e64 v2, v75, v76, s[16:17]
	v_add3_u32 v18, s5, v22, v2
	v_or_b32_e32 v2, s25, v24
	v_mad_u64_u32 v[0:1], s[50:51], v2, s13, v[0:1]
	v_mad_i32_i24 v1, s47, v74, v1
	v_lshl_add_u64 v[2:3], v[18:19], 1, v[0:1]
	v_lshl_add_u64 v[0:1], v[0:1], 0, s[48:49]
	s_add_i32 s4, s4, s12
	s_mov_b32 s5, m0
	s_mov_b32 m0, s4
	s_nop 0
	global_load_lds_dwordx4 v[2:3], off
	s_mov_b32 m0, s5
	v_lshl_add_u64 v[0:1], v[22:23], 1, v[0:1]
	v_lshl_add_u64 v[0:1], v[0:1], 0, s[20:21]
	s_addk_i32 s4, 0x4000
	s_mov_b32 s5, m0
	s_mov_b32 m0, s4
	s_nop 0
	global_load_lds_dwordx4 v[0:1], off
	s_mov_b32 m0, s5
